# prep_unit: L2-warming dummy loads for the next unit's rows issued ahead of the current unit's first loads; on top of conv DPP wave_sum
# speedup vs baseline: 1.0017x; 1.0017x over previous
.LBB0_675:
	v_ashrrev_i32_e32 v65, 3, v64
	v_add_u32_e32 v2, s10, v65
	v_lshlrev_b32_e32 v4, 7, v64
	v_mad_i64_i32 v[22:23], s[6:7], v2, s3, v[20:21]
	v_and_b32_e32 v18, 0x200, v4
	v_lshl_add_u64 v[2:3], v[22:23], 0, v[18:19]
	v_and_b32_e32 v18, 0x180, v4
	v_lshl_add_u64 v[2:3], v[2:3], 0, v[18:19]
	s_add_i32 s98, s35, s68
	s_cmpk_gt_i32 s98, 0x207
	s_cbranch_scc1 .Lnpf_skip_0
	s_mul_hi_i32 s99, s98, 0x7e07e07f
	s_lshr_b32 s100, s99, 31
	s_ashr_i32 s99, s99, 7
	s_add_i32 s99, s99, s100
	s_mul_i32 s100, s99, 0x104
	s_sub_i32 s100, s98, s100
	s_lshl_b32 s101, s100, 6
	s_cmp_lt_i32 s100, 4
	s_cselect_b32 s98, 8, 14
	s_movk_i32 s100, 0xff00
	s_cselect_b32 s100, 0x8000, s100
	s_lshl_b32 s99, s99, s98
	s_add_i32 s99, s99, s101
	s_add_i32 s99, s99, s100
	v_add_u32_e32 v125, s99, v65
	v_and_b32_e32 v124, 7, v64
	v_mad_i64_i32 v[126:127], s[100:101], v125, s3, v[20:21]
	v_lshlrev_b32_e32 v124, 7, v124
	v_mov_b32_e32 v125, 0
	s_mov_b32 s98, 0x800
	s_mov_b32 s99, 0
	v_lshl_add_u64 v[126:127], v[126:127], 0, v[124:125]
	global_load_dword v124, v[126:127], off offset:2112
	global_load_dword v125, v[126:127], off offset:3136
	v_lshl_add_u64 v[126:127], v[126:127], 0, s[98:99]
	global_load_dword v124, v[126:127], off offset:2112
.Lnpf_skip_0:
	global_load_dwordx4 v[28:31], v[2:3], off offset:3136
	global_load_dwordx4 v[32:35], v[2:3], off offset:3152
	global_load_dwordx4 v[68:71], v[2:3], off offset:3168
	global_load_dwordx4 v[72:75], v[2:3], off offset:3184
	global_load_dwordx4 v[14:17], v[2:3], off offset:3200
	global_load_dwordx4 v[10:13], v[2:3], off offset:3216
	global_load_dwordx4 v[6:9], v[2:3], off offset:3232
	s_nop 0
	global_load_dwordx4 v[2:5], v[2:3], off offset:3248
	v_and_b32_e32 v120, 7, v64
	v_lshlrev_b32_e32 v120, 7, v120
	v_mov_b32_e32 v121, 0
	v_lshl_add_u64 v[122:123], v[22:23], 0, v[120:121]
	global_load_dword v124, v[122:123], off offset:2112
	v_add_u32_e32 v126, 0x800, v120
	v_mov_b32_e32 v127, 0
	v_lshl_add_u64 v[126:127], v[22:23], 0, v[126:127]
	global_load_dword v125, v[126:127], off offset:2112
	v_add_u32_e32 v18, s14, v65
	v_add_u32_e32 v18, 0xffffff00, v18
	v_bfe_u32 v66, v64, 2, 1
	v_ashrrev_i32_e32 v25, 3, v18
	v_and_b32_e32 v67, 3, v64
	v_lshlrev_b32_e32 v18, 9, v66
	v_and_b32_e32 v26, -8, v25
	s_cmp_gt_i32 s2, 3
	v_and_b32_e32 v24, 0x1f8, v64
	v_lshl_add_u64 v[22:23], v[22:23], 0, v[18:19]
	v_lshlrev_b32_e32 v18, 7, v67
	v_lshlrev_b32_e32 v26, 1, v26
	s_cselect_b64 s[18:19], -1, 0
	s_cmp_lt_i32 s2, 4
	v_lshl_add_u64 v[22:23], v[22:23], 0, v[18:19]
	v_lshlrev_b32_e32 v18, 3, v24
	v_ashrrev_i32_e32 v27, 31, v26
	v_lshl_or_b32 v24, v25, 1, 14
	s_waitcnt vmcnt(9)
	v_lshlrev_b32_e32 v49, 16, v29
	v_lshlrev_b32_e32 v48, 16, v28
	v_and_b32_e32 v45, 0xffff0000, v29
	v_and_b32_e32 v44, 0xffff0000, v28
	s_waitcnt vmcnt(8)
	v_lshlrev_b32_e32 v61, 16, v33
	v_lshlrev_b32_e32 v60, 16, v32
	v_and_b32_e32 v59, 0xffff0000, v33
	v_and_b32_e32 v58, 0xffff0000, v32
	v_lshlrev_b32_e32 v41, 16, v31
	v_lshlrev_b32_e32 v40, 16, v30
	v_and_b32_e32 v39, 0xffff0000, v31
	v_and_b32_e32 v38, 0xffff0000, v30
	v_lshlrev_b32_e32 v57, 16, v35
	v_lshlrev_b32_e32 v56, 16, v34
	v_and_b32_e32 v55, 0xffff0000, v35
	v_and_b32_e32 v54, 0xffff0000, v34
	s_waitcnt vmcnt(7)
	v_and_b32_e32 v30, 0xffff0000, v70
	v_lshlrev_b32_e32 v37, 16, v69
	v_lshlrev_b32_e32 v36, 16, v68
	v_and_b32_e32 v35, 0xffff0000, v69
	v_and_b32_e32 v34, 0xffff0000, v68
	s_waitcnt vmcnt(6)
	v_lshlrev_b32_e32 v53, 16, v73
	v_lshlrev_b32_e32 v52, 16, v72
	v_and_b32_e32 v51, 0xffff0000, v73
	v_and_b32_e32 v50, 0xffff0000, v72
	v_and_b32_e32 v28, 0xffff0000, v74
	v_lshlrev_b32_e32 v33, 16, v71
	v_lshlrev_b32_e32 v32, 16, v70
	v_lshlrev_b32_e32 v47, 16, v75
	v_lshlrev_b32_e32 v46, 16, v74
	v_and_b32_e32 v43, 0xffff0000, v71
	v_and_b32_e32 v42, 0xffff0000, v75
	s_cbranch_scc1 .LBB0_677
	v_lshl_add_u64 v[80:81], v[26:27], 2, s[8:9]
	v_lshl_add_u64 v[84:85], s[8:9], 0, v[18:19]
	v_ashrrev_i32_e32 v25, 31, v24
	global_load_dwordx4 v[68:71], v[80:81], off
	global_load_dwordx4 v[72:75], v[80:81], off offset:16
	global_load_dwordx4 v[76:79], v[80:81], off offset:32
	global_load_dwordx2 v[96:97], v[80:81], off offset:48
	v_lshl_add_u64 v[92:93], v[84:85], 0, s[12:13]
	v_lshl_add_u64 v[86:87], v[24:25], 2, s[8:9]
	global_load_dwordx4 v[80:83], v[92:93], off offset:48
	global_load_dwordx2 v[98:99], v[86:87], off
	v_add_co_u32_e32 v84, vcc, s26, v84
	s_waitcnt vmcnt(5)
	v_mov_b32_e32 v100, v68
	v_addc_co_u32_e32 v85, vcc, 0, v85, vcc
	global_load_dwordx4 v[84:87], v[84:85], off
	s_nop 0
	global_load_dwordx4 v[88:91], v[92:93], off offset:16
	s_nop 0
	global_load_dwordx4 v[92:95], v[92:93], off offset:32
	s_waitcnt vmcnt(7)
	v_mov_b32_e32 v101, v72
	v_mov_b32_e32 v72, v69
	v_mov_b32_e32 v69, v74
	v_mov_b32_e32 v74, v71
	s_waitcnt vmcnt(5)
	v_mov_b32_e32 v71, v96
	v_mov_b32_e32 v96, v77
	v_mov_b32_e32 v68, v70
	v_mov_b32_e32 v70, v76
	v_mov_b32_e32 v76, v78
	v_pk_mul_f32 v[104:105], v[72:73], v[48:49]
	v_pk_mul_f32 v[106:107], v[74:75], v[44:45]
	v_pk_mul_f32 v[72:73], v[72:73], v[60:61]
	v_pk_mul_f32 v[110:111], v[96:97], v[40:41]
	s_waitcnt vmcnt(3)
	v_mov_b32_e32 v77, v98
	v_mov_b32_e32 v98, v79
	v_pk_mul_f32 v[78:79], v[96:97], v[56:57]
	v_pk_mul_f32 v[74:75], v[74:75], v[58:59]
	v_pk_fma_f32 v[96:97], v[100:101], v[60:61], v[104:105]
	v_pk_fma_f32 v[104:105], v[68:69], v[58:59], v[106:107]
	v_pk_fma_f32 v[48:49], v[100:101], v[48:49], v[72:73] neg_lo:[0,0,1] neg_hi:[0,0,1]
	v_pk_fma_f32 v[72:73], v[70:71], v[56:57], v[110:111]
	v_pk_mul_f32 v[56:57], v[98:99], v[38:39]
	v_pk_fma_f32 v[40:41], v[70:71], v[40:41], v[78:79] neg_lo:[0,0,1] neg_hi:[0,0,1]
	v_pk_mul_f32 v[58:59], v[98:99], v[54:55]
	v_pk_fma_f32 v[44:45], v[68:69], v[44:45], v[74:75] neg_lo:[0,0,1] neg_hi:[0,0,1]
	v_pk_fma_f32 v[74:75], v[76:77], v[54:55], v[56:57]
	v_pk_fma_f32 v[38:39], v[76:77], v[38:39], v[58:59] neg_lo:[0,0,1] neg_hi:[0,0,1]
	v_bfe_u32 v54, v41, 16, 1
	v_bfe_u32 v55, v48, 16, 1
	v_bfe_u32 v56, v49, 16, 1
	v_bfe_u32 v25, v45, 16, 1
	v_bfe_u32 v31, v40, 16, 1
	v_bfe_u32 v57, v105, 16, 1
	v_bfe_u32 v59, v72, 16, 1
	v_bfe_u32 v60, v73, 16, 1
	v_bfe_u32 v69, v39, 16, 1
	v_bfe_u32 v70, v38, 16, 1
	v_add3_u32 v56, v49, v56, s27
	v_add3_u32 v55, v48, v55, s27
	v_add3_u32 v54, v41, v54, s27
	v_bfe_u32 v29, v44, 16, 1
	v_bfe_u32 v61, v96, 16, 1
	v_bfe_u32 v68, v97, 16, 1
	v_add3_u32 v25, v45, v25, s27
	v_add3_u32 v31, v40, v31, s27
	v_bfe_u32 v71, v75, 16, 1
	v_add3_u32 v77, v105, v57, s27
	v_add3_u32 v60, v73, v60, s27
	v_add3_u32 v57, v72, v59, s27
	v_add3_u32 v59, v38, v70, s27
	v_add3_u32 v69, v39, v69, s27
	v_lshrrev_b32_e32 v70, 16, v54
	v_lshrrev_b32_e32 v54, 16, v55
	v_lshrrev_b32_e32 v55, 16, v56
	v_add3_u32 v29, v44, v29, s27
	v_bfe_u32 v76, v74, 16, 1
	v_add3_u32 v68, v97, v68, s27
	v_add3_u32 v61, v96, v61, s27
	v_lshrrev_b32_e32 v31, 16, v31
	v_add3_u32 v71, v75, v71, s27
	v_lshrrev_b32_e32 v78, 16, v57
	v_and_or_b32 v55, v25, s25, v55
	v_and_or_b32 v57, v69, s25, v70
	v_lshrrev_b32_e32 v25, 16, v60
	v_add3_u32 v76, v74, v76, s27
	v_and_or_b32 v54, v29, s25, v54
	v_and_or_b32 v56, v59, s25, v31
	v_lshrrev_b32_e32 v29, 16, v61
	v_lshrrev_b32_e32 v31, 16, v68
	v_and_or_b32 v61, v71, s25, v25
	v_and_or_b32 v59, v77, s25, v31
	v_and_or_b32 v60, v76, s25, v78
	v_bfe_u32 v58, v104, 16, 1
	v_add3_u32 v58, v104, v58, s27
	v_pk_mul_f32 v[102:103], v[82:83], v[42:43]
	v_and_or_b32 v58, v58, s25, v29
	v_mov_b32_e32 v29, v42
	s_waitcnt vmcnt(2)
	v_mov_b32_e32 v68, v84
	s_waitcnt vmcnt(1)
	v_mov_b32_e32 v69, v88
	v_mov_b32_e32 v88, v85
	v_pk_mul_f32 v[70:71], v[88:89], v[36:37]
	v_mov_b32_e32 v31, v43
	v_pk_fma_f32 v[76:77], v[68:69], v[52:53], v[70:71]
	v_mov_b32_e32 v71, v90
	v_mov_b32_e32 v90, v87
	v_mov_b32_e32 v70, v86
	v_pk_mul_f32 v[78:79], v[90:91], v[34:35]
	v_pk_mul_f32 v[52:53], v[88:89], v[52:53]
	v_pk_fma_f32 v[78:79], v[70:71], v[50:51], v[78:79]
	v_pk_mul_f32 v[50:51], v[90:91], v[50:51]
	v_pk_fma_f32 v[36:37], v[68:69], v[36:37], v[52:53] neg_lo:[0,0,1] neg_hi:[0,0,1]
	v_pk_fma_f32 v[34:35], v[70:71], v[34:35], v[50:51] neg_lo:[0,0,1] neg_hi:[0,0,1]
	v_mov_b32_e32 v51, v80
	s_waitcnt vmcnt(0)
	v_mov_b32_e32 v80, v93
	v_mov_b32_e32 v50, v92
	v_pk_mul_f32 v[52:53], v[80:81], v[32:33]
	v_mov_b32_e32 v71, v82
	v_mov_b32_e32 v82, v95
	v_pk_fma_f32 v[84:85], v[50:51], v[46:47], v[52:53]
	v_mul_f32_e32 v52, v94, v28
	v_mov_b32_e32 v70, v94
	v_pk_mul_f32 v[28:29], v[82:83], v[28:29]
	v_mul_f32_e32 v68, v95, v30
	v_pk_fma_f32 v[30:31], v[70:71], v[30:31], v[28:29] neg_lo:[0,0,1] neg_hi:[0,0,1]
	v_pk_mul_f32 v[28:29], v[80:81], v[46:47]
	v_mov_b32_e32 v53, v102
	v_pk_fma_f32 v[32:33], v[50:51], v[32:33], v[28:29] neg_lo:[0,0,1] neg_hi:[0,0,1]
	v_mov_b32_e32 v69, v103
	v_bfe_u32 v47, v32, 16, 1
	v_bfe_u32 v50, v33, 16, 1
	v_bfe_u32 v51, v36, 16, 1
	v_pk_add_f32 v[28:29], v[52:53], v[68:69]
	v_bfe_u32 v25, v31, 16, 1
	v_bfe_u32 v42, v30, 16, 1
	v_bfe_u32 v46, v34, 16, 1
	v_bfe_u32 v52, v37, 16, 1
	v_add3_u32 v50, v33, v50, s27
	v_add3_u32 v47, v32, v47, s27
	v_add3_u32 v51, v36, v51, s27
	v_bfe_u32 v43, v35, 16, 1
	v_add3_u32 v42, v30, v42, s27
	v_add3_u32 v25, v31, v25, s27
	v_add3_u32 v46, v34, v46, s27
	v_add3_u32 v52, v37, v52, s27
	v_lshrrev_b32_e32 v47, 16, v47
	v_lshrrev_b32_e32 v50, 16, v50
	v_lshrrev_b32_e32 v68, 16, v51
	v_add3_u32 v43, v35, v43, s27
	v_lshrrev_b32_e32 v51, 16, v52
	v_and_or_b32 v53, v25, s25, v50
	v_and_or_b32 v52, v42, s25, v47
	v_and_or_b32 v50, v46, s25, v68
	v_bfe_u32 v47, v84, 16, 1
	v_bfe_u32 v68, v85, 16, 1
	v_bfe_u32 v69, v76, 16, 1
	v_bfe_u32 v70, v77, 16, 1
	v_and_or_b32 v51, v43, s25, v51
	v_bfe_u32 v25, v29, 16, 1
	v_bfe_u32 v42, v28, 16, 1
	v_bfe_u32 v43, v79, 16, 1
	v_bfe_u32 v46, v78, 16, 1
	v_add3_u32 v68, v85, v68, s27
	v_add3_u32 v47, v84, v47, s27
	v_add3_u32 v70, v77, v70, s27
	v_add3_u32 v69, v76, v69, s27
	v_add3_u32 v46, v78, v46, s27
	v_add3_u32 v43, v79, v43, s27
	v_add3_u32 v42, v28, v42, s27
	v_add3_u32 v25, v29, v25, s27
	v_lshrrev_b32_e32 v47, 16, v47
	v_lshrrev_b32_e32 v68, 16, v68
	v_lshrrev_b32_e32 v80, 16, v69
	v_lshrrev_b32_e32 v69, 16, v70
	v_and_or_b32 v71, v25, s25, v68
	v_and_or_b32 v70, v42, s25, v47
	v_and_or_b32 v69, v43, s25, v69
	v_and_or_b32 v68, v46, s25, v80
	global_store_dwordx4 v[22:23], v[54:57], off offset:3136
	global_store_dwordx4 v[22:23], v[58:61], off offset:3152
	global_store_dwordx4 v[22:23], v[50:53], off offset:3168
	global_store_dwordx4 v[22:23], v[68:71], off offset:3184
	v_mov_b32_e32 v60, v96
	v_mov_b32_e32 v58, v104
	v_mov_b32_e32 v61, v97
	v_mov_b32_e32 v59, v105
	v_mov_b32_e32 v56, v72
	v_mov_b32_e32 v54, v74
	v_mov_b32_e32 v57, v73
	v_mov_b32_e32 v55, v75
	v_mov_b32_e32 v43, v31
	v_mov_b32_e32 v52, v76
	v_mov_b32_e32 v50, v78
	v_mov_b32_e32 v53, v77
	v_mov_b32_e32 v51, v79
	v_mov_b32_e32 v46, v84
	v_mov_b32_e32 v47, v85
	v_mov_b32_e32 v42, v29

.Lnpf_skip_1:
	global_load_dwordx4 v[28:31], v[2:3], off offset:3136
	global_load_dwordx4 v[32:35], v[2:3], off offset:3152
	global_load_dwordx4 v[68:71], v[2:3], off offset:3168
	global_load_dwordx4 v[72:75], v[2:3], off offset:3184
	global_load_dwordx4 v[14:17], v[2:3], off offset:3200
	global_load_dwordx4 v[10:13], v[2:3], off offset:3216
	global_load_dwordx4 v[6:9], v[2:3], off offset:3232
	s_nop 0
	global_load_dwordx4 v[2:5], v[2:3], off offset:3248
	v_and_b32_e32 v120, 7, v64
	v_lshlrev_b32_e32 v120, 7, v120
	v_mov_b32_e32 v121, 0
	v_lshl_add_u64 v[122:123], v[22:23], 0, v[120:121]
	global_load_dword v124, v[122:123], off offset:2112
	v_add_u32_e32 v126, 0x800, v120
	v_mov_b32_e32 v127, 0
	v_lshl_add_u64 v[126:127], v[22:23], 0, v[126:127]
	global_load_dword v125, v[126:127], off offset:2112
	v_add_u32_e32 v18, s14, v65
	v_add_u32_e32 v18, 0xffffff00, v18
	v_bfe_u32 v66, v64, 2, 1
	v_ashrrev_i32_e32 v25, 3, v18
	v_and_b32_e32 v67, 3, v64
	v_lshlrev_b32_e32 v18, 9, v66
	v_and_b32_e32 v26, -8, v25
	s_cmp_gt_i32 s2, 3
	v_and_b32_e32 v24, 0x1f8, v64
	v_lshl_add_u64 v[22:23], v[22:23], 0, v[18:19]
	v_lshlrev_b32_e32 v18, 7, v67
	v_lshlrev_b32_e32 v26, 1, v26
	s_cselect_b64 s[18:19], -1, 0
	s_cmp_lt_i32 s2, 4
	v_lshl_add_u64 v[22:23], v[22:23], 0, v[18:19]
	v_lshlrev_b32_e32 v18, 3, v24
	v_ashrrev_i32_e32 v27, 31, v26
	v_lshl_or_b32 v24, v25, 1, 14
	s_waitcnt vmcnt(9)
	v_lshlrev_b32_e32 v49, 16, v29
	v_lshlrev_b32_e32 v48, 16, v28
	v_and_b32_e32 v45, 0xffff0000, v29
	v_and_b32_e32 v44, 0xffff0000, v28
	s_waitcnt vmcnt(8)
	v_lshlrev_b32_e32 v61, 16, v33
	v_lshlrev_b32_e32 v60, 16, v32
	v_and_b32_e32 v59, 0xffff0000, v33
	v_and_b32_e32 v58, 0xffff0000, v32
	v_lshlrev_b32_e32 v41, 16, v31
	v_lshlrev_b32_e32 v40, 16, v30
	v_and_b32_e32 v39, 0xffff0000, v31
	v_and_b32_e32 v38, 0xffff0000, v30
	v_lshlrev_b32_e32 v57, 16, v35
	v_lshlrev_b32_e32 v56, 16, v34
	v_and_b32_e32 v55, 0xffff0000, v35
	v_and_b32_e32 v54, 0xffff0000, v34
	s_waitcnt vmcnt(7)
	v_and_b32_e32 v30, 0xffff0000, v70
	v_lshlrev_b32_e32 v37, 16, v69
	v_lshlrev_b32_e32 v36, 16, v68
	v_and_b32_e32 v35, 0xffff0000, v69
	v_and_b32_e32 v34, 0xffff0000, v68
	s_waitcnt vmcnt(6)
	v_lshlrev_b32_e32 v53, 16, v73
	v_lshlrev_b32_e32 v52, 16, v72
	v_and_b32_e32 v51, 0xffff0000, v73
	v_and_b32_e32 v50, 0xffff0000, v72
	v_and_b32_e32 v28, 0xffff0000, v74
	v_lshlrev_b32_e32 v33, 16, v71
	v_lshlrev_b32_e32 v32, 16, v70
	v_lshlrev_b32_e32 v47, 16, v75
	v_lshlrev_b32_e32 v46, 16, v74
	v_and_b32_e32 v43, 0xffff0000, v71
	v_and_b32_e32 v42, 0xffff0000, v75
	s_cbranch_scc1 .LBB0_1919
	v_lshl_add_u64 v[80:81], v[26:27], 2, s[8:9]
	v_lshl_add_u64 v[84:85], s[8:9], 0, v[18:19]
	v_ashrrev_i32_e32 v25, 31, v24
	global_load_dwordx4 v[68:71], v[80:81], off
	global_load_dwordx4 v[72:75], v[80:81], off offset:16
	global_load_dwordx4 v[76:79], v[80:81], off offset:32
	global_load_dwordx2 v[96:97], v[80:81], off offset:48
	v_lshl_add_u64 v[92:93], v[84:85], 0, s[12:13]
	v_lshl_add_u64 v[86:87], v[24:25], 2, s[8:9]
	global_load_dwordx4 v[80:83], v[92:93], off offset:48
	global_load_dwordx2 v[98:99], v[86:87], off
	v_add_co_u32_e32 v84, vcc, s25, v84
	s_waitcnt vmcnt(5)
	v_mov_b32_e32 v100, v68
	v_addc_co_u32_e32 v85, vcc, 0, v85, vcc
	global_load_dwordx4 v[84:87], v[84:85], off
	s_nop 0
	global_load_dwordx4 v[88:91], v[92:93], off offset:16
	s_nop 0
	global_load_dwordx4 v[92:95], v[92:93], off offset:32
	s_waitcnt vmcnt(7)
	v_mov_b32_e32 v101, v72
	v_mov_b32_e32 v72, v69
	v_mov_b32_e32 v69, v74
	v_mov_b32_e32 v74, v71
	s_waitcnt vmcnt(5)
	v_mov_b32_e32 v71, v96
	v_mov_b32_e32 v96, v77
	v_mov_b32_e32 v68, v70
	v_mov_b32_e32 v70, v76
	v_mov_b32_e32 v76, v78
	v_pk_mul_f32 v[104:105], v[72:73], v[48:49]
	v_pk_mul_f32 v[106:107], v[74:75], v[44:45]
	v_pk_mul_f32 v[72:73], v[72:73], v[60:61]
	v_pk_mul_f32 v[110:111], v[96:97], v[40:41]
	s_waitcnt vmcnt(3)
	v_mov_b32_e32 v77, v98
	v_mov_b32_e32 v98, v79
	v_pk_mul_f32 v[78:79], v[96:97], v[56:57]
	v_pk_mul_f32 v[74:75], v[74:75], v[58:59]
	v_pk_fma_f32 v[96:97], v[100:101], v[60:61], v[104:105]
	v_pk_fma_f32 v[104:105], v[68:69], v[58:59], v[106:107]
	v_pk_fma_f32 v[48:49], v[100:101], v[48:49], v[72:73] neg_lo:[0,0,1] neg_hi:[0,0,1]
	v_pk_fma_f32 v[72:73], v[70:71], v[56:57], v[110:111]
	v_pk_mul_f32 v[56:57], v[98:99], v[38:39]
	v_pk_fma_f32 v[40:41], v[70:71], v[40:41], v[78:79] neg_lo:[0,0,1] neg_hi:[0,0,1]
	v_pk_mul_f32 v[58:59], v[98:99], v[54:55]
	v_pk_fma_f32 v[44:45], v[68:69], v[44:45], v[74:75] neg_lo:[0,0,1] neg_hi:[0,0,1]
	v_pk_fma_f32 v[74:75], v[76:77], v[54:55], v[56:57]
	v_pk_fma_f32 v[38:39], v[76:77], v[38:39], v[58:59] neg_lo:[0,0,1] neg_hi:[0,0,1]
	v_bfe_u32 v54, v41, 16, 1
	v_bfe_u32 v55, v48, 16, 1
	v_bfe_u32 v56, v49, 16, 1
	v_bfe_u32 v25, v45, 16, 1
	v_bfe_u32 v31, v40, 16, 1
	v_bfe_u32 v57, v105, 16, 1
	v_bfe_u32 v59, v72, 16, 1
	v_bfe_u32 v60, v73, 16, 1
	v_bfe_u32 v69, v39, 16, 1
	v_bfe_u32 v70, v38, 16, 1
	v_add3_u32 v56, v49, v56, s26
	v_add3_u32 v55, v48, v55, s26
	v_add3_u32 v54, v41, v54, s26
	v_bfe_u32 v29, v44, 16, 1
	v_bfe_u32 v61, v96, 16, 1
	v_bfe_u32 v68, v97, 16, 1
	v_add3_u32 v25, v45, v25, s26
	v_add3_u32 v31, v40, v31, s26
	v_bfe_u32 v71, v75, 16, 1
	v_add3_u32 v77, v105, v57, s26
	v_add3_u32 v60, v73, v60, s26
	v_add3_u32 v57, v72, v59, s26
	v_add3_u32 v59, v38, v70, s26
	v_add3_u32 v69, v39, v69, s26
	v_lshrrev_b32_e32 v70, 16, v54
	v_lshrrev_b32_e32 v54, 16, v55
	v_lshrrev_b32_e32 v55, 16, v56
	v_add3_u32 v29, v44, v29, s26
	v_bfe_u32 v76, v74, 16, 1
	v_add3_u32 v68, v97, v68, s26
	v_add3_u32 v61, v96, v61, s26
	v_lshrrev_b32_e32 v31, 16, v31
	v_add3_u32 v71, v75, v71, s26
	v_lshrrev_b32_e32 v78, 16, v57
	v_and_or_b32 v55, v25, s24, v55
	v_and_or_b32 v57, v69, s24, v70
	v_lshrrev_b32_e32 v25, 16, v60
	v_add3_u32 v76, v74, v76, s26
	v_and_or_b32 v54, v29, s24, v54
	v_and_or_b32 v56, v59, s24, v31
	v_lshrrev_b32_e32 v29, 16, v61
	v_lshrrev_b32_e32 v31, 16, v68
	v_and_or_b32 v61, v71, s24, v25
	v_and_or_b32 v59, v77, s24, v31
	v_and_or_b32 v60, v76, s24, v78
	v_bfe_u32 v58, v104, 16, 1
	v_add3_u32 v58, v104, v58, s26
	v_pk_mul_f32 v[102:103], v[82:83], v[42:43]
	v_and_or_b32 v58, v58, s24, v29
	v_mov_b32_e32 v29, v42
	s_waitcnt vmcnt(2)
	v_mov_b32_e32 v68, v84
	s_waitcnt vmcnt(1)
	v_mov_b32_e32 v69, v88
	v_mov_b32_e32 v88, v85
	v_pk_mul_f32 v[70:71], v[88:89], v[36:37]
	v_mov_b32_e32 v31, v43
	v_pk_fma_f32 v[76:77], v[68:69], v[52:53], v[70:71]
	v_mov_b32_e32 v71, v90
	v_mov_b32_e32 v90, v87
	v_mov_b32_e32 v70, v86
	v_pk_mul_f32 v[78:79], v[90:91], v[34:35]
	v_pk_mul_f32 v[52:53], v[88:89], v[52:53]
	v_pk_fma_f32 v[78:79], v[70:71], v[50:51], v[78:79]
	v_pk_mul_f32 v[50:51], v[90:91], v[50:51]
	v_pk_fma_f32 v[36:37], v[68:69], v[36:37], v[52:53] neg_lo:[0,0,1] neg_hi:[0,0,1]
	v_pk_fma_f32 v[34:35], v[70:71], v[34:35], v[50:51] neg_lo:[0,0,1] neg_hi:[0,0,1]
	v_mov_b32_e32 v51, v80
	s_waitcnt vmcnt(0)
	v_mov_b32_e32 v80, v93
	v_mov_b32_e32 v50, v92
	v_pk_mul_f32 v[52:53], v[80:81], v[32:33]
	v_mov_b32_e32 v71, v82
	v_mov_b32_e32 v82, v95
	v_pk_fma_f32 v[84:85], v[50:51], v[46:47], v[52:53]
	v_mul_f32_e32 v52, v94, v28
	v_mov_b32_e32 v70, v94
	v_pk_mul_f32 v[28:29], v[82:83], v[28:29]
	v_mul_f32_e32 v68, v95, v30
	v_pk_fma_f32 v[30:31], v[70:71], v[30:31], v[28:29] neg_lo:[0,0,1] neg_hi:[0,0,1]
	v_pk_mul_f32 v[28:29], v[80:81], v[46:47]
	v_mov_b32_e32 v53, v102
	v_pk_fma_f32 v[32:33], v[50:51], v[32:33], v[28:29] neg_lo:[0,0,1] neg_hi:[0,0,1]
	v_mov_b32_e32 v69, v103
	v_bfe_u32 v47, v32, 16, 1
	v_bfe_u32 v50, v33, 16, 1
	v_bfe_u32 v51, v36, 16, 1
	v_pk_add_f32 v[28:29], v[52:53], v[68:69]
	v_bfe_u32 v25, v31, 16, 1
	v_bfe_u32 v42, v30, 16, 1
	v_bfe_u32 v46, v34, 16, 1
	v_bfe_u32 v52, v37, 16, 1
	v_add3_u32 v50, v33, v50, s26
	v_add3_u32 v47, v32, v47, s26
	v_add3_u32 v51, v36, v51, s26
	v_bfe_u32 v43, v35, 16, 1
	v_add3_u32 v42, v30, v42, s26
	v_add3_u32 v25, v31, v25, s26
	v_add3_u32 v46, v34, v46, s26
	v_add3_u32 v52, v37, v52, s26
	v_lshrrev_b32_e32 v47, 16, v47
	v_lshrrev_b32_e32 v50, 16, v50
	v_lshrrev_b32_e32 v68, 16, v51
	v_add3_u32 v43, v35, v43, s26
	v_lshrrev_b32_e32 v51, 16, v52
	v_and_or_b32 v53, v25, s24, v50
	v_and_or_b32 v52, v42, s24, v47
	v_and_or_b32 v50, v46, s24, v68
	v_bfe_u32 v47, v84, 16, 1
	v_bfe_u32 v68, v85, 16, 1
	v_bfe_u32 v69, v76, 16, 1
	v_bfe_u32 v70, v77, 16, 1
	v_and_or_b32 v51, v43, s24, v51
	v_bfe_u32 v25, v29, 16, 1
	v_bfe_u32 v42, v28, 16, 1
	v_bfe_u32 v43, v79, 16, 1
	v_bfe_u32 v46, v78, 16, 1
	v_add3_u32 v68, v85, v68, s26
	v_add3_u32 v47, v84, v47, s26
	v_add3_u32 v70, v77, v70, s26
	v_add3_u32 v69, v76, v69, s26
	v_add3_u32 v46, v78, v46, s26
	v_add3_u32 v43, v79, v43, s26
	v_add3_u32 v42, v28, v42, s26
	v_add3_u32 v25, v29, v25, s26
	v_lshrrev_b32_e32 v47, 16, v47
	v_lshrrev_b32_e32 v68, 16, v68
	v_lshrrev_b32_e32 v80, 16, v69
	v_lshrrev_b32_e32 v69, 16, v70
	v_and_or_b32 v71, v25, s24, v68
	v_and_or_b32 v70, v42, s24, v47
	v_and_or_b32 v69, v43, s24, v69
	v_and_or_b32 v68, v46, s24, v80
	global_store_dwordx4 v[22:23], v[54:57], off offset:3136
	global_store_dwordx4 v[22:23], v[58:61], off offset:3152
	global_store_dwordx4 v[22:23], v[50:53], off offset:3168
	global_store_dwordx4 v[22:23], v[68:71], off offset:3184
	v_mov_b32_e32 v60, v96
	v_mov_b32_e32 v58, v104
	v_mov_b32_e32 v61, v97
	v_mov_b32_e32 v59, v105
	v_mov_b32_e32 v56, v72
	v_mov_b32_e32 v54, v74
	v_mov_b32_e32 v57, v73
	v_mov_b32_e32 v55, v75
	v_mov_b32_e32 v43, v31
	v_mov_b32_e32 v52, v76
	v_mov_b32_e32 v50, v78
	v_mov_b32_e32 v53, v77
	v_mov_b32_e32 v51, v79
	v_mov_b32_e32 v46, v84
	v_mov_b32_e32 v47, v85
	v_mov_b32_e32 v42, v29
